# SSD scan: next-chunk prefetch addresses from a scalar base plus per-thread offsets; staged-tile loads spread through the compute section
# speedup vs baseline: 1.0138x; 1.0004x over previous
; __device__ __forceinline__ void ssd_item(const Params& P, const int pass, const int item, const int wvi) {
;     ...
;   {
;     const int chp = dir ? 0 : (nch - 1);
;     const size_t tbp = (size_t)b * S + (size_t)chp * 128;
; #pragma unroll
;     for (int pt = 0; pt < 4; pt += 2) {
;       const uint2 ya = make_uint2(yp[pt][0], yp[pt][1]), yb2 = make_uint2(yp[pt + 1][0], yp[pt + 1][1]);
;       *(uint4*)(yout + (tbp + it * 16 + fr) * DI + h * 64 + (pt + (fq & 1)) * 16 + (fq & ~1) * 4) = swap_pair(ya, yb2);
;     }
;   }
;   __builtin_amdgcn_s_setprio(0);
;   __syncthreads();
.LBB0_438:
	s_and_b64 s[0:1], s[8:9], exec
	v_readlane_b32 s0, v243, 41
	s_cselect_b32 s18, s0, 0
	s_lshl_b64 s[0:1], s[18:19], 7
	s_add_u32 s0, s29, s0
	v_readlane_b32 s2, v242, 12
	s_addc_u32 s1, s2, s1
	s_waitcnt vmcnt(0)
	v_mov_b32_e32 v1, s1
	v_or_b32_e32 v0, s0, v210
	v_readlane_b32 s0, v242, 8
	v_lshlrev_b64 v[0:1], 13, v[0:1]
	v_readlane_b32 s1, v242, 9
	v_lshlrev_b32_e32 v144, 1, v164
	v_permlane16_swap_b32_e32 v96, v92
	v_lshl_add_u64 v[0:1], s[0:1], 0, v[0:1]
	v_readlane_b32 s0, v242, 10
	v_readlane_b32 s1, v242, 11
	s_mov_b32 s1, s19
	v_permlane16_swap_b32_e32 v97, v93
	v_lshl_add_u64 v[0:1], v[0:1], 0, s[0:1]
	v_lshl_add_u64 v[0:1], v[0:1], 0, v[144:145]
	v_lshlrev_b32_e32 v144, 1, v166
	v_lshl_add_u64 v[0:1], v[0:1], 0, v[144:145]
	v_mov_b32_e32 v98, v92
	v_mov_b32_e32 v99, v93
	v_permlane16_swap_b32_e32 v88, v90
	v_permlane16_swap_b32_e32 v89, v91
	global_store_dwordx4 v[0:1], v[96:99], off
	global_store_dwordx4 v[0:1], v[88:91], off offset:64
	s_setprio 0
	v_readlane_b32 s50, v244, 57
	v_readlane_b32 s52, v244, 59
	v_readlane_b32 s56, v243, 0
	v_readlane_b32 s58, v243, 5
	v_readlane_b32 s62, v243, 7
	v_readlane_b32 s64, v243, 30
	v_readlane_b32 s66, v243, 9
	v_readlane_b32 s72, v243, 15
	v_readlane_b32 s76, v243, 19
	v_readlane_b32 s26, v243, 62
	v_readlane_b32 s48, v244, 56
	v_readlane_b32 s51, v244, 58
	v_readlane_b32 s53, v244, 60
	v_readlane_b32 s49, v244, 62
	v_readlane_b32 s54, v244, 63
	v_readlane_b32 s57, v243, 1
	v_readlane_b32 s59, v243, 6
	v_readlane_b32 s55, v243, 28
	v_readlane_b32 s60, v243, 29
	v_readlane_b32 s63, v243, 8
	v_readlane_b32 s65, v243, 31
	v_readlane_b32 s67, v243, 10
	v_readlane_b32 s61, v243, 11
	v_readlane_b32 s68, v243, 12
	v_readlane_b32 s69, v243, 13
	v_readlane_b32 s70, v243, 14
	v_readlane_b32 s73, v243, 16
	v_readlane_b32 s71, v243, 17
	v_readlane_b32 s74, v243, 18
	v_readlane_b32 s77, v243, 20
	v_readlane_b32 s75, v243, 21
	v_readlane_b32 s78, v243, 22
	v_readlane_b32 s79, v243, 23
	v_readlane_b32 s80, v243, 24
	v_readlane_b32 s81, v243, 25
	v_readlane_b32 s82, v243, 26
	v_readlane_b32 s83, v243, 27
	v_readlane_b32 s84, v243, 32
	s_movk_i32 s85, 0x3000
	s_mov_b32 s88, 0x800000
	s_movk_i32 s89, 0x2000
	s_movk_i32 s90, 0xd000
	s_movk_i32 s91, 0x1800
	s_mov_b32 s93, 0x32700000
	s_mov_b32 s96, 0x26700000
	s_movk_i32 s97, 0x101
	s_mov_b64 s[46:47], 0x100
	v_readlane_b32 s24, v243, 60
	v_readlane_b32 s25, v243, 61
	v_readlane_b32 s27, v243, 63
	s_barrier

; __device__ __forceinline__ void ssd_item(const Params& P, const int pass, const int item, const int wvi) {
;   unsigned char* ws = wsp_plain(P);
;   const int tid = tidx(wvi), lane = tid & 63, w = wvi, fr = lane & 15, fq = lane >> 4;
;   const int S = (pass == 0) ? 2048 : 16384, nch = S >> 7;
;   const int dir = item & 1, h = (item >> 1) & 63, b = item >> 7, g = h >> 3, dh = dir * 64 + h;
;   constexpr int SSD_SET = 128 * LDP * 2 + 128 * LDX * 2 + 64 * LDP * 2 + 4 * 128 * 4;
;   const u16* xc = (const u16*)(ws + OFF_RB);
;   const u16* G = (const u16*)(ws + OFF_G);
;   const float* dtt = (const float*)(ws + ((tid < 128) ? OFF_DTT : (tid < 256) ? OFF_CUM : (tid < 384) ? OFF_WW : OFF_EE)) + (size_t)dh * PT + (tid & 127);
;   u16* yout = dir ? (u16*)(ws + OFF_YB) : (u16*)(ws + OFF_RA);
;   const int it = (w < 4) ? w : 11 - w;
;   const int kk_lo = dir ? (it >> 1) : 0, kk_hi = dir ? 3 : (it >> 1);
;   f32x4 st[4];
; #pragma unroll
;   for (int i = 0; i < 4; ++i) st[i] = f32x4{0.f, 0.f, 0.f, 0.f};
;   uint4 rb0, rb1, rb2, rb3, rx0, rx1, rc0, rc1, rc2, rc3, rg0, rg1, rg2, rg3;
;   float rdt = 0.f;
;   const uint4 z4 = make_uint4(0u, 0u, 0u, 0u);
;   rg0 = z4; rg1 = z4; rg2 = z4; rg3 = z4;
.LBB0_631:
	s_ashr_i32 s0, s12, 3
	v_readlane_b32 s1, v242, 5
	s_add_i32 s1, s0, s1
	s_and_b32 s6, s0, 1
	s_bfe_i32 s4, s0, 0x10000
	s_lshl_b32 s0, s1, 2
	s_lshl_b32 s3, s1, 3
	v_readlane_b32 s5, v242, 7
	s_and_b32 s2, s12, 7
	s_or_b32 s3, s3, s5
	s_and_b32 s20, s0, 56
	v_readlane_b32 s5, v245, 16
	s_or_b32 s7, s20, s2
	s_ashr_i32 s0, s3, 7
	s_and_b32 s16, s4, s5
	s_bfe_u32 s18, s1, 0x30001
	s_cmp_eq_u32 s6, 0
	s_cselect_b64 s[8:9], -1, 0
	s_and_b64 s[2:3], s[8:9], exec
	v_readlane_b32 s1, v243, 41
	s_cselect_b32 s17, s5, 3
	s_and_b32 s2, s4, s1
	s_ashr_i32 s1, s0, 31
	v_readlane_b32 s3, v243, 56
	s_lshl_b64 s[4:5], s[0:1], s3
	s_mov_b32 s3, s19
	v_add_u32_e32 v211, s48, v46
	s_lshl_b64 s[0:1], s[2:3], 7
	s_add_u32 s2, s4, s0
	v_add_u32_e32 v8, 0x400, v211
	s_addc_u32 s3, s5, s1
	v_ashrrev_i32_e32 v146, 4, v211
	v_readlane_b32 s0, v245, 25
	v_ashrrev_i32_e32 v150, 4, v8
	v_ashrrev_i32_e32 v147, 31, v146
	v_readlane_b32 s1, v245, 26
	v_ashrrev_i32_e32 v151, 31, v150
	v_lshl_add_u64 v[0:1], s[2:3], 0, v[146:147]
	v_mov_b64_e32 v[24:25], s[0:1]
	v_lshl_add_u64 v[8:9], s[2:3], 0, v[150:151]
	v_mad_u64_u32 v[2:3], s[0:1], v0, s85, v[24:25]
	v_mad_u64_u32 v[10:11], s[10:11], v8, s85, v[24:25]
	s_lshl_b32 s0, s20, 5
	s_mov_b32 s1, s19
	v_mad_i32_i24 v11, v9, s85, v11
	v_add_u32_e32 v21, 0x200, v211
	v_lshl_add_u64 v[8:9], v[10:11], 0, s[0:1]
	v_add_u32_e32 v10, 0x600, v211
	v_mad_i32_i24 v3, v1, s85, v3
	v_lshlrev_b32_e32 v20, 3, v211
	v_ashrrev_i32_e32 v148, 4, v21
	v_ashrrev_i32_e32 v152, 4, v10
	v_ashrrev_i32_e32 v154, 3, v211
	v_lshl_add_u64 v[0:1], v[2:3], 0, s[0:1]
	v_and_b32_e32 v2, 0x78, v20
	v_ashrrev_i32_e32 v149, 31, v148
	v_ashrrev_i32_e32 v153, 31, v152
	v_ashrrev_i32_e32 v155, 31, v154
	v_lshlrev_b32_e32 v144, 1, v2
	v_lshl_add_u64 v[2:3], s[2:3], 0, v[148:149]
	v_lshl_add_u64 v[10:11], s[2:3], 0, v[152:153]
	v_lshl_add_u64 v[16:17], s[2:3], 0, v[154:155]
	v_mad_u64_u32 v[4:5], s[10:11], v2, s85, v[24:25]
	v_mad_u64_u32 v[12:13], s[10:11], v10, s85, v[24:25]
	v_mad_u64_u32 v[18:19], s[10:11], v16, s85, v[24:25]
	v_mad_i32_i24 v19, v17, s85, v19
	s_lshl_b32 s10, s7, 7
	s_mov_b32 s11, s19
	v_ashrrev_i32_e32 v158, 3, v21
	v_lshl_add_u64 v[16:17], v[18:19], 0, s[10:11]
	v_and_b32_e32 v18, 56, v20
	v_ashrrev_i32_e32 v159, 31, v158
	v_lshl_add_u64 v[0:1], v[0:1], 0, v[144:145]
	v_mad_i32_i24 v5, v3, s85, v5
	v_lshlrev_b32_e32 v156, 1, v18
	v_lshl_add_u64 v[18:19], s[2:3], 0, v[158:159]
	v_add_co_u32_e32 v0, vcc, s89, v0
	v_lshl_add_u64 v[2:3], v[4:5], 0, s[0:1]
	v_mad_u64_u32 v[20:21], s[12:13], v18, s85, v[24:25]
	v_addc_co_u32_e32 v1, vcc, 0, v1, vcc
	v_lshl_add_u64 v[2:3], v[2:3], 0, v[144:145]
	v_mad_i32_i24 v21, v19, s85, v21
	v_and_b32_e32 v210, 15, v46
	v_add_co_u32_e32 v4, vcc, s89, v2
	v_lshl_add_u64 v[18:19], v[20:21], 0, s[10:11]
	s_add_u32 s10, s2, s55
	v_addc_co_u32_e32 v5, vcc, 0, v3, vcc
	v_lshl_add_u64 v[8:9], v[8:9], 0, v[144:145]
	v_mad_i32_i24 v13, v11, s85, v13
	s_addc_u32 s11, s3, s60
	v_or_b32_e32 v26, s10, v210
	v_add_co_u32_e32 v8, vcc, s89, v8
	v_lshl_add_u64 v[10:11], v[12:13], 0, s[0:1]
	s_mul_i32 s12, s11, 0x3000
	v_mad_u64_u32 v[24:25], s[10:11], v26, s85, v[24:25]
	v_lshrrev_b32_e32 v26, 1, v211
	v_addc_co_u32_e32 v9, vcc, 0, v9, vcc
	v_lshl_add_u64 v[10:11], v[10:11], 0, v[144:145]
	v_add_u32_e32 v25, s12, v25
	v_and_b32_e32 v212, 24, v26
	v_add_co_u32_e32 v12, vcc, s89, v10
	v_lshl_add_u64 v[24:25], v[24:25], 0, s[0:1]
	v_lshlrev_b32_e32 v160, 1, v212
	v_mov_b32_e32 v161, v145
	v_addc_co_u32_e32 v13, vcc, 0, v11, vcc
	v_lshl_add_u64 v[24:25], v[24:25], 0, v[160:161]
	s_mov_b64 s[0:1], 0x2800
	v_mov_b32_e32 v157, v145
	v_lshl_add_u64 v[26:27], v[24:25], 0, s[0:1]
	v_add_co_u32_e32 v24, vcc, 0x2000, v24
	v_lshl_add_u64 v[16:17], v[16:17], 0, v[156:157]
	v_lshl_add_u64 v[20:21], v[18:19], 0, v[156:157]
	v_addc_co_u32_e32 v25, vcc, 0, v25, vcc
	s_mul_i32 s32, s2, 0x3000
	v_readlane_b32 s98, v245, 25
	s_nop 3
	s_add_u32 s32, s32, s98
	v_subrev_u32_e32 v247, s32, v0
	v_subrev_u32_e32 v248, s32, v4
	v_subrev_u32_e32 v249, s32, v8
	v_subrev_u32_e32 v250, s32, v12
	v_subrev_u32_e32 v251, s32, v16
	v_subrev_u32_e32 v252, s32, v20
	v_subrev_u32_e32 v253, s32, v26
	global_load_dwordx4 v[0:3], v[0:1], off
	s_nop 0
	global_load_dwordx4 v[4:7], v[4:5], off
	s_nop 0
	global_load_dwordx4 v[8:11], v[8:9], off
	s_nop 0
	global_load_dwordx4 v[12:15], v[12:13], off
	s_nop 0
	global_load_dwordx4 v[16:19], v[16:17], off
	s_nop 0
	global_load_dwordx4 v[20:23], v[20:21], off
	s_nop 0
	global_load_dwordx4 v[36:39], v[26:27], off offset:64
	global_load_dwordx4 v[28:31], v[26:27], off offset:128
	global_load_dwordx4 v[72:75], v[24:25], off offset:2048
	s_nop 0
	global_load_dwordx4 v[24:27], v[26:27], off offset:192
	s_cmp_lt_i32 s16, 1
	s_cselect_b64 s[0:1], -1, 0
	s_cmp_gt_i32 s17, -1
	s_cselect_b64 s[10:11], -1, 0
	s_and_b64 s[0:1], s[0:1], s[10:11]
	v_cndmask_b32_e64 v32, 0, 1, s[0:1]
	v_cmp_ne_u32_e64 s[10:11], 1, v32
	s_andn2_b64 vcc, exec, s[0:1]
	s_cbranch_vccnz .LBB0_633
	s_lshr_b64 s[0:1], s[2:3], 4
	s_or_b32 s0, s0, s18
	s_lshl_b64 s[0:1], s[0:1], 7
	s_add_u32 s0, s0, s55
	s_addc_u32 s1, s1, s60
	v_mov_b32_e32 v33, s1
	v_or_b32_e32 v32, s0, v210
	v_lshlrev_b64 v[32:33], 8, v[32:33]
	v_lshl_add_u64 v[32:33], s[64:65], 0, v[32:33]
	v_lshl_add_u64 v[32:33], v[32:33], 0, v[160:161]
	global_load_dwordx4 v[84:87], v[32:33], off
	s_branch .LBB0_634

; __device__ __forceinline__ void ssd_item(const Params& P, const int pass, const int item, const int wvi) {
;     ...
;   const float* dtt = (const float*)(ws + ((tid < 128) ? OFF_DTT : (tid < 256) ? OFF_CUM : (tid < 384) ? OFF_WW : OFF_EE)) + (size_t)dh * PT + (tid & 127);
;   u16* yout = dir ? (u16*)(ws + OFF_YB) : (u16*)(ws + OFF_RA);
;   const int it = (w < 4) ? w : 11 - w;
;   const int kk_lo = dir ? (it >> 1) : 0, kk_hi = dir ? 3 : (it >> 1);
;   f32x4 st[4];
; #pragma unroll
;   for (int i = 0; i < 4; ++i) st[i] = f32x4{0.f, 0.f, 0.f, 0.f};
;   uint4 rb0, rb1, rb2, rb3, rx0, rx1, rc0, rc1, rc2, rc3, rg0, rg1, rg2, rg3;
;   float rdt = 0.f;
;   const uint4 z4 = make_uint4(0u, 0u, 0u, 0u);
;   rg0 = z4; rg1 = z4; rg2 = z4; rg3 = z4;
.LBB0_646:
	s_movk_i32 s1, 0x180
	v_cmp_gt_u32_e32 vcc, s1, v211
	s_movk_i32 s1, 0xff
	s_movk_i32 s23, 0x7f
	v_cndmask_b32_e32 v44, v203, v204, vcc
	v_cmp_lt_u32_e32 vcc, s1, v211
	s_and_b64 s[20:21], s[8:9], exec
	s_mov_b32 s1, 0x35f00000
	v_cndmask_b32_e32 v44, v205, v44, vcc
	v_cmp_lt_i32_e32 vcc, s23, v211
	s_cselect_b32 s1, 0xa700000, s1
	s_lshl_b32 s6, s6, 22
	s_lshl_b32 s7, s7, 16
	v_cndmask_b32_e32 v44, v206, v44, vcc
	v_mov_b32_e32 v45, v145
	s_or_b32 s18, s7, s6
	v_and_b32_e32 v48, 0x7f, v211
	v_lshl_add_u64 v[44:45], s[94:95], 0, v[44:45]
	s_add_u32 s6, s94, s1
	v_lshl_add_u64 v[44:45], v[44:45], 0, s[18:19]
	s_addc_u32 s7, s95, 0
	v_lshlrev_b32_e32 v48, 2, v48
	v_mov_b32_e32 v49, v145
	s_lshl_b32 s18, s0, 1
	v_lshl_add_u64 v[162:163], v[44:45], 0, v[48:49]
	s_movk_i32 s1, 0x90
	s_add_u32 s0, s6, s18
	v_lshrrev_b32_e32 v47, 4, v211
	v_lshl_add_u64 v[44:45], s[2:3], 2, v[162:163]
	v_mul_lo_u32 v217, v154, s1
	v_mul_lo_u32 v218, v158, s1
	v_writelane_b32 v242, s6, 8
	s_addc_u32 s1, s7, 0
	v_readlane_b32 s2, v245, 25
	v_readlane_b32 s3, v245, 26
	s_add_u32 s2, s2, s18
	v_mov_b32_e32 v171, s60
	v_or_b32_e32 v170, s55, v210
	v_mov_b32_e32 v161, v145
	v_lshlrev_b32_e32 v47, 2, v47
	global_load_dword v228, v[44:45], off
	s_addc_u32 s3, s3, 0
	v_mov_b32_e32 v157, v145
	v_lshl_add_u64 v[48:49], s[64:65], 0, v[160:161]
	s_waitcnt vmcnt(14)
	v_lshrrev_b32_e32 v52, 2, v210
	v_lshlrev_b32_e32 v44, 2, v46
	v_and_b32_e32 v164, 8, v47
	v_and_b32_e32 v166, 16, v46
	v_lshlrev_b64 v[46:47], 8, v[170:171]
	v_lshl_add_u64 v[168:169], s[2:3], 0, v[156:157]
	s_add_u32 s2, s4, s55
	v_lshl_add_u64 v[172:173], v[48:49], 0, v[46:47]
	v_or_b32_e32 v48, v212, v52
	v_cmp_le_i32_e32 vcc, v212, v170
	v_writelane_b32 v242, s7, 9
	s_mov_b32 s6, s18
	s_addc_u32 s3, s5, s60
	v_mul_u32_u24_e32 v220, 0x90, v48
	v_mul_u32_u24_e32 v221, 0x110, v48
	v_cndmask_b32_e64 v48, 0, 1, vcc
	v_cmp_ge_i32_e32 vcc, v212, v170
	v_writelane_b32 v242, s6, 10
	v_lshlrev_b32_e32 v50, 1, v164
	v_mov_b32_e32 v51, v145
	s_cmp_lt_i32 s16, 1
	v_cndmask_b32_e64 v49, 0, 1, vcc
	v_writelane_b32 v242, s7, 11
	v_lshl_add_u64 v[50:51], s[0:1], 0, v[50:51]
	s_cselect_b64 s[0:1], -1, 0
	s_cmp_gt_i32 s17, -1
	v_cndmask_b32_e64 v48, v49, v48, s[8:9]
	v_and_b32_e32 v53, 12, v44
	v_writelane_b32 v242, s3, 12
	v_mov_b32_e32 v45, s3
	s_mov_b32 s29, s2
	v_or_b32_e32 v44, s2, v210
	s_cselect_b64 s[2:3], -1, 0
	v_and_b32_e32 v48, 1, v48
	s_and_b64 s[6:7], s[0:1], s[2:3]
	v_cmp_eq_u32_e64 s[2:3], 1, v48
	v_or_b32_e32 v48, 1, v212
	v_cmp_ge_i32_e32 vcc, v48, v170
	v_writelane_b32 v242, s2, 13
	v_or_b32_e32 v222, 32, v212
	v_cndmask_b32_e64 v48, 0, 1, vcc
	v_cmp_lt_i32_e32 vcc, v212, v170
	v_writelane_b32 v242, s3, 14
	s_and_b64 s[0:1], s[8:9], exec
	v_cndmask_b32_e64 v49, 0, 1, vcc
	v_cndmask_b32_e64 v48, v48, v49, s[8:9]
	v_and_b32_e32 v48, 1, v48
	v_cmp_eq_u32_e64 s[2:3], 1, v48
	v_or_b32_e32 v48, 2, v212
	v_cmp_le_i32_e32 vcc, v48, v170
	v_writelane_b32 v242, s2, 15
	s_cselect_b32 s0, 31, 0
	v_cndmask_b32_e64 v49, 0, 1, vcc
	v_cmp_ge_i32_e32 vcc, v48, v170
	v_writelane_b32 v242, s3, 16
	s_cmp_lt_i32 s16, 2
	v_cndmask_b32_e64 v48, 0, 1, vcc
	v_cndmask_b32_e64 v48, v48, v49, s[8:9]
	v_and_b32_e32 v48, 1, v48
	v_cmp_eq_u32_e64 s[2:3], 1, v48
	v_or_b32_e32 v48, 3, v212
	v_cmp_le_i32_e32 vcc, v48, v170
	v_writelane_b32 v242, s2, 17
	s_movk_i32 s20, 0x110
	v_cndmask_b32_e64 v49, 0, 1, vcc
	v_cmp_ge_i32_e32 vcc, v48, v170
	v_writelane_b32 v242, s3, 18
	v_mul_lo_u32 v213, v146, s20
	v_cndmask_b32_e64 v48, 0, 1, vcc
	v_cndmask_b32_e64 v48, v48, v49, s[8:9]
	v_and_b32_e32 v48, 1, v48
	v_cmp_eq_u32_e64 s[2:3], 1, v48
	v_or_b32_e32 v48, 4, v212
	v_cmp_le_i32_e32 vcc, v48, v170
	v_writelane_b32 v242, s2, 19
	v_mul_lo_u32 v214, v148, s20
	v_cndmask_b32_e64 v49, 0, 1, vcc
	v_cmp_ge_i32_e32 vcc, v48, v170
	v_writelane_b32 v242, s3, 20
	v_mul_lo_u32 v215, v150, s20
	v_cndmask_b32_e64 v48, 0, 1, vcc
	v_cndmask_b32_e64 v48, v48, v49, s[8:9]
	v_and_b32_e32 v48, 1, v48
	v_cmp_eq_u32_e64 s[2:3], 1, v48
	v_or_b32_e32 v48, 5, v212
	v_cmp_le_i32_e32 vcc, v48, v170
	v_writelane_b32 v242, s2, 21
	v_mul_lo_u32 v216, v152, s20
	v_cndmask_b32_e64 v49, 0, 1, vcc
	v_cmp_ge_i32_e32 vcc, v48, v170
	v_writelane_b32 v242, s3, 22
	v_mad_u32_u24 v219, v210, s20, v207
	v_cndmask_b32_e64 v48, 0, 1, vcc
	v_cndmask_b32_e64 v48, v48, v49, s[8:9]
	v_and_b32_e32 v48, 1, v48
	v_cmp_eq_u32_e64 s[2:3], 1, v48
	v_or_b32_e32 v48, 6, v212
	v_cmp_le_i32_e32 vcc, v48, v170
	v_writelane_b32 v242, s2, 23
	v_or_b32_e32 v225, 64, v212
	v_cndmask_b32_e64 v49, 0, 1, vcc
	v_cmp_ge_i32_e32 vcc, v48, v170
	v_writelane_b32 v242, s3, 24
	v_or_b32_e32 v229, 0x60, v212
	v_cndmask_b32_e64 v48, 0, 1, vcc
	v_cndmask_b32_e64 v48, v48, v49, s[8:9]
	v_and_b32_e32 v48, 1, v48
	v_cmp_eq_u32_e64 s[2:3], 1, v48
	v_or_b32_e32 v48, 7, v212
	v_cmp_le_i32_e32 vcc, v48, v170
	v_writelane_b32 v242, s2, 25
	v_lshl_add_u64 v[46:47], s[64:65], 0, v[46:47]
	v_cndmask_b32_e64 v49, 0, 1, vcc
	v_cmp_ge_i32_e32 vcc, v48, v170
	v_writelane_b32 v242, s3, 26
	s_cselect_b64 s[2:3], -1, 0
	v_cndmask_b32_e64 v48, 0, 1, vcc
	v_cndmask_b32_e64 v48, v48, v49, s[8:9]
	v_and_b32_e32 v48, 1, v48
	v_cmp_eq_u32_e64 s[30:31], 1, v48
	v_or_b32_e32 v48, v222, v52
	v_cmp_le_i32_e32 vcc, v222, v170
	v_mul_u32_u24_e32 v223, 0x90, v48
	v_mul_u32_u24_e32 v224, 0x110, v48
	v_cndmask_b32_e64 v48, 0, 1, vcc
	v_cmp_ge_i32_e32 vcc, v222, v170
	s_cmp_gt_i32 s17, 0
	s_cselect_b64 s[20:21], -1, 0
	v_cndmask_b32_e64 v49, 0, 1, vcc
	v_cndmask_b32_e64 v48, v49, v48, s[8:9]
	v_and_b32_e32 v48, 1, v48
	s_and_b64 s[82:83], s[2:3], s[20:21]
	v_cmp_eq_u32_e64 s[20:21], 1, v48
	v_or_b32_e32 v48, 33, v212
	v_cmp_le_i32_e32 vcc, v48, v170
; __device__ __forceinline__ void ssd_item(const Params& P, const int pass, const int item, const int wvi) {
;     ...
;   u16* yout = dir ? (u16*)(ws + OFF_YB) : (u16*)(ws + OFF_RA);
;   const int it = (w < 4) ? w : 11 - w;
;   const int kk_lo = dir ? (it >> 1) : 0, kk_hi = dir ? 3 : (it >> 1);
;   f32x4 st[4];
; #pragma unroll
;   for (int i = 0; i < 4; ++i) st[i] = f32x4{0.f, 0.f, 0.f, 0.f};
;   uint4 rb0, rb1, rb2, rb3, rx0, rx1, rc0, rc1, rc2, rc3, rg0, rg1, rg2, rg3;
;   float rdt = 0.f;
;   const uint4 z4 = make_uint4(0u, 0u, 0u, 0u);
;   rg0 = z4; rg1 = z4; rg2 = z4; rg3 = z4;
;     ...
;   unsigned yp[4][2];
; #pragma unroll
;   for (int pt = 0; pt < 4; ++pt) { yp[pt][0] = 0u; yp[pt][1] = 0u; }
	v_lshlrev_b64 v[44:45], 13, v[44:45]
	v_lshl_add_u64 v[44:45], v[50:51], 0, v[44:45]
	v_cndmask_b32_e64 v49, 0, 1, vcc
	v_cmp_ge_i32_e32 vcc, v48, v170
	s_and_b64 s[2:3], s[8:9], exec
	v_or_b32_e32 v51, 0x64, v212
	v_cndmask_b32_e64 v48, 0, 1, vcc
	v_cndmask_b32_e64 v48, v48, v49, s[8:9]
	v_and_b32_e32 v48, 1, v48
	v_cmp_eq_u32_e64 s[36:37], 1, v48
	v_or_b32_e32 v48, 34, v212
	v_cmp_le_i32_e32 vcc, v48, v170
	s_cselect_b32 s1, 63, 32
	s_cmp_lt_i32 s16, 3
	v_cndmask_b32_e64 v49, 0, 1, vcc
	v_cmp_ge_i32_e32 vcc, v48, v170
	s_cselect_b64 s[2:3], -1, 0
	s_cmp_gt_i32 s17, 1
	v_cndmask_b32_e64 v48, 0, 1, vcc
	v_cndmask_b32_e64 v48, v48, v49, s[8:9]
	v_and_b32_e32 v48, 1, v48
	v_cmp_eq_u32_e64 s[38:39], 1, v48
	v_or_b32_e32 v48, 35, v212
	v_cmp_le_i32_e32 vcc, v48, v170
	v_or_b32_e32 v54, 0x65, v212
	s_cselect_b64 s[24:25], -1, 0
	v_cndmask_b32_e64 v49, 0, 1, vcc
	v_cmp_ge_i32_e32 vcc, v48, v170
	s_and_b64 s[2:3], s[2:3], s[24:25]
	v_or_b32_e32 v56, 0x66, v212
	v_cndmask_b32_e64 v48, 0, 1, vcc
	v_cndmask_b32_e64 v48, v48, v49, s[8:9]
	v_and_b32_e32 v48, 1, v48
	v_cmp_eq_u32_e64 s[40:41], 1, v48
	v_or_b32_e32 v48, 36, v212
	v_cmp_le_i32_e32 vcc, v48, v170
	s_and_b64 s[24:25], s[8:9], exec
	s_cselect_b32 s24, 0x5f, 64
	v_cndmask_b32_e64 v49, 0, 1, vcc
	v_cmp_ge_i32_e32 vcc, v48, v170
	s_cmp_lt_i32 s16, 4
	v_or_b32_e32 v58, 0x67, v212
	v_cndmask_b32_e64 v48, 0, 1, vcc
	v_cndmask_b32_e64 v48, v48, v49, s[8:9]
	v_and_b32_e32 v48, 1, v48
	v_cmp_eq_u32_e64 s[42:43], 1, v48
	v_or_b32_e32 v48, 37, v212
	v_cmp_le_i32_e32 vcc, v48, v170
	s_cselect_b64 s[26:27], -1, 0
	s_cmp_gt_i32 s17, 2
	v_cndmask_b32_e64 v49, 0, 1, vcc
	v_cmp_ge_i32_e32 vcc, v48, v170
	s_cselect_b64 s[16:17], -1, 0
	s_and_b64 s[96:97], s[26:27], s[16:17]
	v_cndmask_b32_e64 v48, 0, 1, vcc
	v_cndmask_b32_e64 v48, v48, v49, s[8:9]
	v_and_b32_e32 v48, 1, v48
	v_cmp_eq_u32_e64 s[44:45], 1, v48
	v_or_b32_e32 v48, 38, v212
	v_cmp_le_i32_e32 vcc, v48, v170
	s_and_b64 s[16:17], s[8:9], exec
	s_cselect_b32 s25, s23, 0x60
	v_cndmask_b32_e64 v49, 0, 1, vcc
	v_cmp_ge_i32_e32 vcc, v48, v170
	v_mov_b32_e32 v112, 0
	v_mov_b32_e32 v96, 0
	v_cndmask_b32_e64 v48, 0, 1, vcc
	v_cndmask_b32_e64 v48, v48, v49, s[8:9]
	v_and_b32_e32 v48, 1, v48
	v_cmp_eq_u32_e64 s[46:47], 1, v48
	v_or_b32_e32 v48, 39, v212
	v_cmp_le_i32_e32 vcc, v48, v170
	v_mul_u32_u24_e32 v157, 0x110, v210
	v_lshl_add_u64 v[176:177], v[46:47], 0, v[160:161]
	s_mov_b64 s[100:101], s[64:65]
	v_subrev_u32_e32 v254, s64, v176
	v_cndmask_b32_e64 v49, 0, 1, vcc
	v_cmp_ge_i32_e32 vcc, v48, v170
	s_mov_b32 s23, 0
	s_lshl_b32 s18, s22, 1
	v_cndmask_b32_e64 v48, 0, 1, vcc
	v_cndmask_b32_e64 v48, v48, v49, s[8:9]
	v_and_b32_e32 v48, 1, v48
	v_cmp_eq_u32_e64 s[48:49], 1, v48
	v_or_b32_e32 v48, v225, v52
	v_cmp_le_i32_e32 vcc, v225, v170
	v_mul_u32_u24_e32 v226, 0x90, v48
	v_mul_u32_u24_e32 v227, 0x110, v48
	v_cndmask_b32_e64 v48, 0, 1, vcc
	v_cmp_ge_i32_e32 vcc, v225, v170
	v_lshlrev_b32_e32 v232, 1, v53
	s_lshl_b32 s16, s0, 2
	v_cndmask_b32_e64 v49, 0, 1, vcc
	v_cndmask_b32_e64 v48, v49, v48, s[8:9]
	v_and_b32_e32 v48, 1, v48
	v_cmp_eq_u32_e64 s[50:51], 1, v48
	v_or_b32_e32 v48, 0x41, v212
	v_cmp_le_i32_e32 vcc, v48, v170
	s_lshl_b32 s17, s1, 2
	s_lshl_b32 s88, s24, 2
	v_cndmask_b32_e64 v49, 0, 1, vcc
	v_cmp_ge_i32_e32 vcc, v48, v170
	s_lshl_b32 s89, s25, 2
	s_mov_b32 s93, s34
	v_cndmask_b32_e64 v48, 0, 1, vcc
	v_cndmask_b32_e64 v48, v48, v49, s[8:9]
	v_and_b32_e32 v48, 1, v48
	v_cmp_eq_u32_e64 s[52:53], 1, v48
	v_or_b32_e32 v48, 0x42, v212
	v_cmp_le_i32_e32 vcc, v48, v170
	v_mov_b32_e32 v97, v96
	v_mov_b32_e32 v92, v96
	v_cndmask_b32_e64 v49, 0, 1, vcc
	v_cmp_ge_i32_e32 vcc, v48, v170
	v_mov_b32_e32 v93, v96
	v_mov_b32_e32 v88, v96
	v_cndmask_b32_e64 v48, 0, 1, vcc
	v_cndmask_b32_e64 v48, v48, v49, s[8:9]
	v_and_b32_e32 v48, 1, v48
	v_cmp_eq_u32_e64 s[54:55], 1, v48
	v_or_b32_e32 v48, 0x43, v212
	v_cmp_le_i32_e32 vcc, v48, v170
	v_mov_b32_e32 v89, v96
	v_mov_b32_e32 v90, v96
	v_cndmask_b32_e64 v49, 0, 1, vcc
	v_cmp_ge_i32_e32 vcc, v48, v170
	v_mov_b32_e32 v91, v96
	v_mov_b32_e32 v113, v112
	v_cndmask_b32_e64 v48, 0, 1, vcc
	v_cndmask_b32_e64 v48, v48, v49, s[8:9]
	v_and_b32_e32 v48, 1, v48
	v_cmp_eq_u32_e64 s[56:57], 1, v48
	v_or_b32_e32 v48, 0x44, v212
	v_cmp_le_i32_e32 vcc, v48, v170
	v_mov_b32_e32 v114, v112
	v_mov_b32_e32 v115, v112
	v_cndmask_b32_e64 v49, 0, 1, vcc
	v_cmp_ge_i32_e32 vcc, v48, v170
	v_mov_b32_e32 v100, v112
	v_mov_b32_e32 v101, v112
	v_cndmask_b32_e64 v48, 0, 1, vcc
	v_cndmask_b32_e64 v48, v48, v49, s[8:9]
	v_and_b32_e32 v48, 1, v48
	v_cmp_eq_u32_e64 s[58:59], 1, v48
	v_or_b32_e32 v48, 0x45, v212
	v_cmp_le_i32_e32 vcc, v48, v170
	v_mov_b32_e32 v102, v112
	v_mov_b32_e32 v103, v112
	v_cndmask_b32_e64 v49, 0, 1, vcc
	v_cmp_ge_i32_e32 vcc, v48, v170
	v_mov_b32_e32 v104, v112
	v_mov_b32_e32 v105, v112
	v_cndmask_b32_e64 v48, 0, 1, vcc
	v_cndmask_b32_e64 v48, v48, v49, s[8:9]
	v_and_b32_e32 v48, 1, v48
	v_cmp_eq_u32_e64 s[60:61], 1, v48
	v_or_b32_e32 v48, 0x46, v212
	v_cmp_le_i32_e32 vcc, v48, v170
	v_mov_b32_e32 v106, v112
	v_mov_b32_e32 v107, v112
	v_cndmask_b32_e64 v49, 0, 1, vcc
	v_cmp_ge_i32_e32 vcc, v48, v170
	v_mov_b32_e32 v108, v112
	v_mov_b32_e32 v109, v112
	v_cndmask_b32_e64 v48, 0, 1, vcc
	v_cndmask_b32_e64 v48, v48, v49, s[8:9]
	v_and_b32_e32 v48, 1, v48
	v_cmp_eq_u32_e64 s[62:63], 1, v48
	v_or_b32_e32 v48, 0x47, v212
	v_cmp_le_i32_e32 vcc, v48, v170
	v_mov_b32_e32 v110, v112
	v_mov_b32_e32 v111, v112
	v_cndmask_b32_e64 v49, 0, 1, vcc
; #define SSD_STB(i, RB) do { const int q = tid + NTHR * (i), row = q >> 4, c16 = q & 15; \
;       *(uint4*)(Bs + row * LDP + c16 * 8) = RB; } while (0)
; #define SSD_STX(i, RX) do { const int q = tid + NTHR * (i), row = q >> 3, c8 = q & 7; \
;       *(uint4*)(Xs + row * LDX + c8 * 8) = RX; } while (0)
; __device__ __forceinline__ void ssd_item(const Params& P, const int pass, const int item, const int wvi) {
;     ...
;   for (int c = 0; c < nch; ++c) {
;     u16* Bs = (u16*)(smem + (c & 1) * SSD_SET);
;     u16* Xs = Bs + 128 * LDP;
;     u16* Sb = Xs + 128 * LDX;
;     float* fdt = (float*)(Sb + 64 * LDP);
;     float* fcum = fdt + 128;
;     float* fww = fcum + 128;
;     float* fee = fww + 128;
; #pragma unroll
;     for (int pt = 0; pt < 4; ++pt) {
;       uint2 o; o.x = pk2(st[pt][0], st[pt][1]); o.y = pk2(st[pt][2], st[pt][3]);
;       *(uint2*)(Sb + (pt * 16 + fr) * LDP + w * 16 + fq * 4) = o;
;     }
;     SSD_STB(0, rb0); SSD_STB(1, rb1); SSD_STB(2, rb2); SSD_STB(3, rb3);
;     SSD_STX(0, rx0); SSD_STX(1, rx1);
;     fdt[tid] = rdt;
;     const bf16x8 cf0 = __builtin_bit_cast(bf16x8, rc0), cf1 = __builtin_bit_cast(bf16x8, rc1),
;                  cf2 = __builtin_bit_cast(bf16x8, rc2), cf3 = __builtin_bit_cast(bf16x8, rc3);
;     const uint4 gq0 = rg0, gq1 = rg1, gq2 = rg2, gq3 = rg3;
;     __syncthreads();
;     if (c > 0) {
;       const int chp = dir ? (nch - c) : (c - 1);
;       const size_t tbp = (size_t)b * S + (size_t)chp * 128;
; #pragma unroll
;       for (int pt = 0; pt < 4; pt += 2) {
;         const uint2 ya = make_uint2(yp[pt][0], yp[pt][1]), yb2 = make_uint2(yp[pt + 1][0], yp[pt + 1][1]);
;         *(uint4*)(yout + (tbp + it * 16 + fr) * DI + h * 64 + (pt + (fq & 1)) * 16 + (fq & ~1) * 4) = swap_pair(ya, yb2);
;       }
;     }
;     SSD_ISSUE((c + 1 < nch) ? (c + 1) : c);
	v_cmp_ge_i32_e32 vcc, v48, v170
	s_nop 1
	v_cndmask_b32_e64 v48, 0, 1, vcc
	v_cndmask_b32_e64 v48, v48, v49, s[8:9]
	v_and_b32_e32 v48, 1, v48
	v_cmp_eq_u32_e64 s[64:65], 1, v48
	v_or_b32_e32 v48, v229, v52
	v_cmp_le_i32_e32 vcc, v229, v170
	v_mul_u32_u24_e32 v230, 0x90, v48
	v_mul_u32_u24_e32 v231, 0x110, v48
	v_cndmask_b32_e64 v48, 0, 1, vcc
	v_cmp_ge_i32_e32 vcc, v229, v170
	s_nop 1
	v_cndmask_b32_e64 v49, 0, 1, vcc
	v_cndmask_b32_e64 v48, v49, v48, s[8:9]
	v_and_b32_e32 v48, 1, v48
	v_cmp_eq_u32_e64 s[66:67], 1, v48
	v_or_b32_e32 v48, 0x61, v212
	v_cmp_le_i32_e32 vcc, v48, v170
	s_nop 1
	v_cndmask_b32_e64 v49, 0, 1, vcc
	v_cmp_ge_i32_e32 vcc, v48, v170
	s_nop 1
	v_cndmask_b32_e64 v48, 0, 1, vcc
	v_cndmask_b32_e64 v48, v48, v49, s[8:9]
	v_and_b32_e32 v48, 1, v48
	v_cmp_eq_u32_e64 s[68:69], 1, v48
	v_or_b32_e32 v48, 0x62, v212
	v_cmp_le_i32_e32 vcc, v48, v170
	s_nop 1
	v_cndmask_b32_e64 v49, 0, 1, vcc
	v_cmp_ge_i32_e32 vcc, v48, v170
	s_nop 1
	v_cndmask_b32_e64 v48, 0, 1, vcc
	v_cndmask_b32_e64 v48, v48, v49, s[8:9]
	v_or_b32_e32 v49, 0x63, v212
	v_cmp_le_i32_e32 vcc, v49, v170
	v_and_b32_e32 v48, 1, v48
	v_cmp_eq_u32_e64 s[70:71], 1, v48
	v_cndmask_b32_e64 v50, 0, 1, vcc
	v_cmp_ge_i32_e32 vcc, v49, v170
	s_nop 1
	v_cndmask_b32_e64 v49, 0, 1, vcc
	v_cmp_le_i32_e32 vcc, v51, v170
	v_cndmask_b32_e64 v48, v49, v50, s[8:9]
	v_and_b32_e32 v50, 1, v48
	v_cndmask_b32_e64 v52, 0, 1, vcc
	v_cmp_ge_i32_e32 vcc, v51, v170
	v_mov_b32_e32 v49, v145
	v_cmp_eq_u32_e64 s[72:73], 1, v50
	v_cndmask_b32_e64 v51, 0, 1, vcc
	v_cmp_le_i32_e32 vcc, v54, v170
	v_cndmask_b32_e64 v48, v51, v52, s[8:9]
	v_and_b32_e32 v51, 1, v48
	v_cndmask_b32_e64 v55, 0, 1, vcc
	v_cmp_ge_i32_e32 vcc, v54, v170
	v_cmp_eq_u32_e64 s[74:75], 1, v51
	s_nop 0
	v_cndmask_b32_e64 v54, 0, 1, vcc
	v_cmp_le_i32_e32 vcc, v56, v170
	v_cndmask_b32_e64 v48, v54, v55, s[8:9]
	v_and_b32_e32 v52, 1, v48
	v_cndmask_b32_e64 v57, 0, 1, vcc
	v_cmp_ge_i32_e32 vcc, v56, v170
	v_cmp_eq_u32_e64 s[76:77], 1, v52
	s_nop 0
	v_cndmask_b32_e64 v56, 0, 1, vcc
	v_cmp_le_i32_e32 vcc, v58, v170
	v_cndmask_b32_e64 v48, v56, v57, s[8:9]
	v_and_b32_e32 v54, 1, v48
	v_cndmask_b32_e64 v59, 0, 1, vcc
	v_cmp_ge_i32_e32 vcc, v58, v170
	v_cmp_eq_u32_e64 s[78:79], 1, v54
	s_nop 0
	v_cndmask_b32_e64 v58, 0, 1, vcc
	v_cndmask_b32_e64 v48, v58, v59, s[8:9]
	v_and_b32_e32 v55, 1, v48
	v_lshlrev_b32_e32 v48, 1, v166
	v_lshl_add_u64 v[174:175], v[44:45], 0, v[48:49]
	v_cmp_eq_u32_e64 s[80:81], 1, v55
.LBB0_647:
	s_bitcmp1_b32 s23, 0
	s_cselect_b32 s0, 0x11c00, 0
	s_add_i32 s26, s0, 32
	v_readlane_b32 s0, v246, 55
	s_add_i32 s27, s26, s0
	v_add3_u32 v46, s27, v212, v157
	v_cvt_pk_bf16_f32 v45, v114, v115
	v_cvt_pk_bf16_f32 v44, v112, v113
	ds_write_b64 v46, v[44:45] offset:53248
	v_cvt_pk_bf16_f32 v45, v102, v103
	v_cvt_pk_bf16_f32 v44, v100, v101
	ds_write_b64 v46, v[44:45] offset:57600
	v_cvt_pk_bf16_f32 v45, v106, v107
	v_cvt_pk_bf16_f32 v44, v104, v105
	v_add_u32_e32 v47, 0xd000, v46
	ds_write_b64 v46, v[44:45] offset:61952
	v_cvt_pk_bf16_f32 v45, v110, v111
	v_cvt_pk_bf16_f32 v44, v108, v109
	ds_write_b64 v47, v[44:45] offset:13056
	v_add3_u32 v44, s26, v213, v144
	s_waitcnt vmcnt(5)
	ds_write_b128 v44, v[0:3]
	v_add3_u32 v0, s26, v214, v144
	s_waitcnt vmcnt(4)
	ds_write_b128 v0, v[4:7]
	v_add3_u32 v0, s26, v215, v144
	s_waitcnt vmcnt(3)
	ds_write_b128 v0, v[8:11]
	v_add3_u32 v0, s26, v216, v144
	s_waitcnt vmcnt(2)
	ds_write_b128 v0, v[12:15]
	v_add3_u32 v0, s26, v217, v156
	s_add_i32 s22, s26, 0x11400
	s_waitcnt vmcnt(1)
	ds_write_b128 v0, v[16:19] offset:34816
	v_add3_u32 v0, s26, v218, v156
	s_waitcnt vmcnt(0)
	ds_write_b128 v0, v[20:23] offset:34816
	v_lshl_add_u32 v0, v211, 2, s22
	s_cmp_eq_u32 s23, 0
	s_waitcnt vmcnt(0)
	ds_write_b32 v0, v228
	s_waitcnt lgkmcnt(0)
	s_barrier
	s_cbranch_scc1 .LBB0_649
	s_add_i32 s24, s23, -1
	s_and_b64 s[0:1], s[8:9], exec
	s_cselect_b32 s0, s24, s93
	s_ashr_i32 s1, s0, 31
	s_lshl_b64 s[0:1], s[0:1], 20
	v_permlane16_swap_b32_e32 v96, v92
	v_permlane16_swap_b32_e32 v97, v93
	v_lshl_add_u64 v[0:1], v[174:175], 0, s[0:1]
	v_mov_b32_e32 v98, v92
	v_mov_b32_e32 v99, v93
	v_permlane16_swap_b32_e32 v88, v90
	v_permlane16_swap_b32_e32 v89, v91
	global_store_dwordx4 v[0:1], v[96:99], off
	global_store_dwordx4 v[0:1], v[88:91], off offset:64
.LBB0_649:
	s_add_i32 s35, s23, 1
	s_cmp_lt_u32 s35, s34
	s_cselect_b32 s23, s35, s23
	v_readlane_b32 s0, v243, 41
	s_sub_i32 s24, s0, s23
	s_and_b64 s[0:1], s[8:9], exec
	s_cselect_b32 s0, s23, s24
	s_ashr_i32 s1, s0, 31
	s_lshl_b64 s[0:1], s[0:1], 7
	s_add_u32 s0, s0, s4
	v_readlane_b32 s24, v245, 25
	s_addc_u32 s1, s1, s5
	v_readlane_b32 s25, v245, 26
	s_nop 1
	s_mul_hi_u32 s99, s0, 0x3000
	s_mul_i32 s98, s0, 0x3000
	s_add_u32 s98, s98, s24
	s_addc_u32 s99, s99, s25
	global_load_dwordx4 v[44:47], v253, s[98:99] offset:64
	global_load_dwordx4 v[48:51], v253, s[98:99] offset:128
	global_load_dwordx4 v[60:63], v253, s[98:99]
	global_load_dwordx4 v[52:55], v253, s[98:99] offset:192
	s_and_b64 vcc, exec, s[10:11]
	v_mov_b64_e32 v[56:57], v[84:85]
	v_mov_b64_e32 v[58:59], v[86:87]
	s_cbranch_vccnz .LBB0_653
	s_lshr_b64 s[24:25], s[0:1], 4
	s_add_u32 s24, s24, s84
	s_addc_u32 s25, s25, s85
	s_lshl_b64 s[24:25], s[24:25], 15
	s_add_u32 s24, s24, s100
	s_addc_u32 s25, s25, s101
	global_load_dwordx4 v[56:59], v254, s[24:25]
	s_and_b64 vcc, exec, s[12:13]
	v_mov_b64_e32 v[64:65], v[76:77]
	v_mov_b64_e32 v[66:67], v[78:79]
	s_cbranch_vccz .LBB0_654

.LBB0_652:
	s_lshr_b64 s[24:25], s[0:1], 4
	s_add_u32 s24, s24, s84
	s_addc_u32 s25, s25, s85
	s_lshl_b64 s[24:25], s[24:25], 15
	s_add_u32 s24, s24, s100
	s_addc_u32 s25, s25, s101
	global_load_dwordx4 v[68:71], v254, s[24:25] offset:128
	s_andn2_b64 vcc, exec, s[90:91]
	v_mov_b64_e32 v[80:81], v[32:33]
	v_mov_b64_e32 v[82:83], v[34:35]
	s_cbranch_vccz .LBB0_656
	s_branch .LBB0_657

.LBB0_654:
	s_lshr_b64 s[24:25], s[0:1], 4
	s_add_u32 s24, s24, s84
	s_addc_u32 s25, s25, s85
	s_lshl_b64 s[24:25], s[24:25], 15
	s_add_u32 s24, s24, s100
	s_addc_u32 s25, s25, s101
	global_load_dwordx4 v[64:67], v254, s[24:25] offset:64
	s_and_b64 vcc, exec, s[14:15]
	v_mov_b64_e32 v[68:69], v[40:41]
	v_mov_b64_e32 v[70:71], v[42:43]
	s_cbranch_vccz .LBB0_652

.LBB0_656:
	s_lshr_b64 s[24:25], s[0:1], 4
	s_add_u32 s24, s24, s84
	s_addc_u32 s25, s25, s85
	s_lshl_b64 s[24:25], s[24:25], 15
	s_add_u32 s24, s24, s100
	s_addc_u32 s25, s25, s101
	global_load_dwordx4 v[80:83], v254, s[24:25] offset:192

; __device__ __forceinline__ void ssd_item(const Params& P, const int pass, const int item, const int wvi) {
;     ...
; #pragma unroll
;     for (int kk = 0; kk < 4; ++kk) {
;       const int s0 = kk * 32 + fq * 8;
;       bf16x8 xf[4];
; #pragma unroll
;       for (int pt = 0; pt < 4; ++pt) {
;         const u16* xa = Xs + (kk * 32 + fq * 8 + (fr >> 2)) * LDX + pt * 16 + (fr & 3) * 4;
;         xf[pt] = cat8(ldtr(xa), ldtr(xa + 4 * LDX));
;       }
;       {
;         const u16* ba = Bs + (kk * 32 + fq * 8 + (fr >> 2)) * LDP + w * 16 + (fr & 3) * 4;
;         const s16x4 b0 = ldtr(ba), b1 = ldtr(ba + 4 * LDP);
;         const float4 wa = *(const float4*)(fww + s0), wb = *(const float4*)(fww + s0 + 4);
;         const bf16x8 af = pack8(bf2f((u16)b0[0]) * wa.x, bf2f((u16)b0[1]) * wa.y, bf2f((u16)b0[2]) * wa.z, bf2f((u16)b0[3]) * wa.w,
;                                 bf2f((u16)b1[0]) * wb.x, bf2f((u16)b1[1]) * wb.y, bf2f((u16)b1[2]) * wb.z, bf2f((u16)b1[3]) * wb.w);
; #pragma unroll
;         for (int pt = 0; pt < 4; ++pt) st[pt] = __builtin_amdgcn_mfma_f32_16x16x32_bf16(af, xf[pt], st[pt], 0, 0, 0);
;       }
;       if (kk >= kk_lo && kk <= kk_hi) {
;         const uint4 gq = (kk == 0) ? gq0 : (kk == 1) ? gq1 : (kk == 2) ? gq2 : gq3;
;         const float gv[8] = {bflo(gq.x), bfhi(gq.x), bflo(gq.y), bfhi(gq.y), bflo(gq.z), bfhi(gq.z), bflo(gq.w), bfhi(gq.w)};
;         float mv[8];
;         if (kk == (it >> 1)) {
;           const float4 ca = *(const float4*)(fcum + s0), cb = *(const float4*)(fcum + s0 + 4);
;           const float4 da = *(const float4*)(fdt + s0), db = *(const float4*)(fdt + s0 + 4);
;           const float cs[8] = {ca.x, ca.y, ca.z, ca.w, cb.x, cb.y, cb.z, cb.w};
;           const float ds[8] = {da.x, da.y, da.z, da.w, db.x, db.y, db.z, db.w};
; #pragma unroll
;           for (int e = 0; e < 8; ++e) {
;             const int ss = s0 + e;
;             const bool ok = dir ? (ss >= ii) : (ss <= ii);
;             mv[e] = ok ? gv[e] * __expf(cum_i - cs[e]) * ds[e] : 0.f;
;           }
;         } else {
;           const float ai = __expf(cum_i - fcum[dir ? kk * 32 : kk * 32 + 31]);
;           const float4 ea = *(const float4*)(fee + s0), eb = *(const float4*)(fee + s0 + 4);
;           mv[0] = gv[0] * ai * ea.x; mv[1] = gv[1] * ai * ea.y; mv[2] = gv[2] * ai * ea.z; mv[3] = gv[3] * ai * ea.w;
.LBB0_666:
	global_load_dwordx4 v[0:3], v247, s[98:99]
	global_load_dwordx4 v[4:7], v248, s[98:99]
	v_lshl_add_u32 v128, v212, 1, s26
	v_add_u32_e32 v234, v128, v157
	ds_read_b128 v[100:103], v234 offset:53248
	ds_read_b128 v[124:127], v234 offset:57600
	v_add_u32_e32 v236, v128, v219
	v_add_u32_e32 v182, v235, v223
	v_add_u32_e32 v136, v233, v224
	s_waitcnt lgkmcnt(1)
	v_mfma_f32_16x16x32_bf16 v[120:123], v[100:103], v[72:75], 0
	ds_read_b128 v[100:103], v234 offset:61952
	ds_read_b128 v[132:135], v236 offset:53248
	ds_read_b64_tr_b16 v[130:131], v182 offset:35392
	ds_read_b64_tr_b16 v[128:129], v136
	v_lshl_add_u32 v137, v222, 2, s25
	s_waitcnt lgkmcnt(4)
	v_mfma_f32_16x16x32_bf16 v[124:127], v[124:127], v[72:75], 0
	s_andn2_b64 vcc, exec, s[82:83]
	s_waitcnt lgkmcnt(0)
	v_and_b32_e32 v143, 0xffff0000, v128
	v_mfma_f32_16x16x32_bf16 v[100:103], v[100:103], v[72:75], 0
	v_lshlrev_b32_e32 v142, 16, v128
	v_mfma_f32_16x16x32_bf16 v[72:75], v[132:135], v[72:75], 0
	ds_read_b128 v[132:135], v137
	ds_read_b64_tr_b16 v[140:141], v136 offset:1088
	ds_read_b128 v[136:139], v137 offset:16
	s_waitcnt lgkmcnt(2)
	v_pk_mul_f32 v[132:133], v[132:133], v[142:143]
	s_nop 0
	v_cvt_pk_bf16_f32 v178, v132, v133
	v_and_b32_e32 v133, 0xffff0000, v129
	v_lshlrev_b32_e32 v132, 16, v129
	v_pk_mul_f32 v[128:129], v[134:135], v[132:133]
	s_nop 0
	v_cvt_pk_bf16_f32 v179, v128, v129
	s_waitcnt lgkmcnt(1)
	v_and_b32_e32 v129, 0xffff0000, v140
	v_lshlrev_b32_e32 v128, 16, v140
	s_waitcnt lgkmcnt(0)
	v_pk_mul_f32 v[128:129], v[136:137], v[128:129]
	s_nop 0
	v_cvt_pk_bf16_f32 v180, v128, v129
	v_and_b32_e32 v129, 0xffff0000, v141
	v_lshlrev_b32_e32 v128, 16, v141
	v_pk_mul_f32 v[128:129], v[138:139], v[128:129]
	s_nop 0
	v_cvt_pk_bf16_f32 v181, v128, v129
	ds_read_b64_tr_b16 v[128:129], v182 offset:34816
	ds_read_b64_tr_b16 v[140:141], v182 offset:34848
	ds_read_b64_tr_b16 v[136:137], v182 offset:34880
	ds_read_b64_tr_b16 v[132:133], v182 offset:34912
	ds_read_b64_tr_b16 v[142:143], v182 offset:35424
	ds_read_b64_tr_b16 v[138:139], v182 offset:35456
	ds_read_b64_tr_b16 v[134:135], v182 offset:35488
	s_waitcnt lgkmcnt(6)
	v_mfma_f32_16x16x32_bf16 v[112:115], v[178:181], v[128:131], v[112:115]
	s_waitcnt lgkmcnt(2)
	v_mfma_f32_16x16x32_bf16 v[116:119], v[178:181], v[140:143], v[116:119]
	s_waitcnt lgkmcnt(1)
	v_mfma_f32_16x16x32_bf16 v[104:107], v[178:181], v[136:139], v[104:107]
	s_waitcnt lgkmcnt(0)
	v_mfma_f32_16x16x32_bf16 v[108:111], v[178:181], v[132:135], v[108:111]
	s_cbranch_vccnz .LBB0_674
	v_readlane_b32 s0, v245, 12
	v_readlane_b32 s1, v245, 13
	v_lshlrev_b32_e32 v182, 16, v76
	v_and_b32_e32 v183, 0xffff0000, v76
	v_lshlrev_b32_e32 v180, 16, v77
	v_and_b32_e32 v181, 0xffff0000, v77
	v_lshlrev_b32_e32 v178, 16, v78
	v_and_b32_e32 v179, 0xffff0000, v78
	v_lshlrev_b32_e32 v76, 16, v79
	v_and_b32_e32 v77, 0xffff0000, v79
	s_andn2_b64 vcc, exec, s[0:1]
	s_mov_b64 s[0:1], -1
	s_cbranch_vccnz .LBB0_669
	s_add_i32 s0, s23, s17
	v_mov_b32_e32 v78, s0
	ds_read_b32 v78, v78
	v_lshl_add_u32 v79, v222, 2, s24
	ds_read_b128 v[184:187], v79
	ds_read_b128 v[188:191], v79 offset:16
	s_mov_b64 s[0:1], 0
	s_waitcnt lgkmcnt(2)
	v_sub_f32_e32 v78, v161, v78
	v_mul_f32_e32 v78, 0x3fb8aa3b, v78
	v_exp_f32_e32 v78, v78
	s_nop 0
	v_pk_mul_f32 v[192:193], v[78:79], v[182:183] op_sel_hi:[0,1]
	v_pk_mul_f32 v[194:195], v[78:79], v[180:181] op_sel_hi:[0,1]
	v_pk_mul_f32 v[238:239], v[78:79], v[178:179] op_sel_hi:[0,1]
	v_pk_mul_f32 v[240:241], v[78:79], v[76:77] op_sel_hi:[0,1]
	s_waitcnt lgkmcnt(1)
	v_pk_mul_f32 v[78:79], v[184:185], v[192:193]
	v_pk_mul_f32 v[184:185], v[186:187], v[194:195]
	s_waitcnt lgkmcnt(0)
	v_pk_mul_f32 v[186:187], v[238:239], v[188:189]
	v_pk_mul_f32 v[188:189], v[240:241], v[190:191]

; __device__ __forceinline__ void ssd_item(const Params& P, const int pass, const int item, const int wvi) {
;     ...
; #pragma unroll
;     for (int kk = 0; kk < 4; ++kk) {
;       const int s0 = kk * 32 + fq * 8;
;       bf16x8 xf[4];
; #pragma unroll
;       for (int pt = 0; pt < 4; ++pt) {
;         const u16* xa = Xs + (kk * 32 + fq * 8 + (fr >> 2)) * LDX + pt * 16 + (fr & 3) * 4;
;         xf[pt] = cat8(ldtr(xa), ldtr(xa + 4 * LDX));
;       }
;       {
;         const u16* ba = Bs + (kk * 32 + fq * 8 + (fr >> 2)) * LDP + w * 16 + (fr & 3) * 4;
;         const s16x4 b0 = ldtr(ba), b1 = ldtr(ba + 4 * LDP);
;         const float4 wa = *(const float4*)(fww + s0), wb = *(const float4*)(fww + s0 + 4);
;         const bf16x8 af = pack8(bf2f((u16)b0[0]) * wa.x, bf2f((u16)b0[1]) * wa.y, bf2f((u16)b0[2]) * wa.z, bf2f((u16)b0[3]) * wa.w,
;                                 bf2f((u16)b1[0]) * wb.x, bf2f((u16)b1[1]) * wb.y, bf2f((u16)b1[2]) * wb.z, bf2f((u16)b1[3]) * wb.w);
; #pragma unroll
;         for (int pt = 0; pt < 4; ++pt) st[pt] = __builtin_amdgcn_mfma_f32_16x16x32_bf16(af, xf[pt], st[pt], 0, 0, 0);
;       }
;       if (kk >= kk_lo && kk <= kk_hi) {
;         const uint4 gq = (kk == 0) ? gq0 : (kk == 1) ? gq1 : (kk == 2) ? gq2 : gq3;
;         const float gv[8] = {bflo(gq.x), bfhi(gq.x), bflo(gq.y), bfhi(gq.y), bflo(gq.z), bfhi(gq.z), bflo(gq.w), bfhi(gq.w)};
;         float mv[8];
;         if (kk == (it >> 1)) {
;           const float4 ca = *(const float4*)(fcum + s0), cb = *(const float4*)(fcum + s0 + 4);
;           const float4 da = *(const float4*)(fdt + s0), db = *(const float4*)(fdt + s0 + 4);
;           const float cs[8] = {ca.x, ca.y, ca.z, ca.w, cb.x, cb.y, cb.z, cb.w};
;           const float ds[8] = {da.x, da.y, da.z, da.w, db.x, db.y, db.z, db.w};
; #pragma unroll
;           for (int e = 0; e < 8; ++e) {
;             const int ss = s0 + e;
;             const bool ok = dir ? (ss >= ii) : (ss <= ii);
;             mv[e] = ok ? gv[e] * __expf(cum_i - cs[e]) * ds[e] : 0.f;
;           }
;         } else {
;           const float ai = __expf(cum_i - fcum[dir ? kk * 32 : kk * 32 + 31]);
;           const float4 ea = *(const float4*)(fee + s0), eb = *(const float4*)(fee + s0 + 4);
;           mv[0] = gv[0] * ai * ea.x; mv[1] = gv[1] * ai * ea.y; mv[2] = gv[2] * ai * ea.z; mv[3] = gv[3] * ai * ea.w;
.LBB0_674:
	global_load_dwordx4 v[8:11], v249, s[98:99]
	global_load_dwordx4 v[12:15], v250, s[98:99]
	ds_read_b128 v[76:79], v234 offset:53312
	ds_read_b128 v[128:131], v234 offset:57664
	ds_read_b128 v[132:135], v234 offset:62016
	ds_read_b128 v[136:139], v236 offset:53312
	v_add_u32_e32 v178, v235, v226
	s_andn2_b64 vcc, exec, s[2:3]
	s_waitcnt lgkmcnt(3)
	v_mfma_f32_16x16x32_bf16 v[76:79], v[76:79], v[36:39], v[120:123]
	s_waitcnt lgkmcnt(2)
	v_mfma_f32_16x16x32_bf16 v[120:123], v[128:131], v[36:39], v[124:127]
	v_add_u32_e32 v128, v233, v227
	s_waitcnt lgkmcnt(1)
	v_mfma_f32_16x16x32_bf16 v[100:103], v[132:135], v[36:39], v[100:103]
	v_lshl_add_u32 v134, v225, 2, s25
	ds_read_b64_tr_b16 v[126:127], v178 offset:35392
	ds_read_b64_tr_b16 v[124:125], v128
	ds_read_b64_tr_b16 v[132:133], v128 offset:1088
	ds_read_b128 v[128:131], v134
	s_waitcnt lgkmcnt(4)
	v_mfma_f32_16x16x32_bf16 v[36:39], v[136:139], v[36:39], v[72:75]
	s_waitcnt lgkmcnt(2)
	v_and_b32_e32 v135, 0xffff0000, v124
	s_nop 0
	ds_read_b128 v[72:75], v134 offset:16
	v_lshlrev_b32_e32 v134, 16, v124
	s_waitcnt lgkmcnt(1)
	v_pk_mul_f32 v[128:129], v[128:129], v[134:135]
	s_nop 0
	v_cvt_pk_bf16_f32 v140, v128, v129
	v_and_b32_e32 v129, 0xffff0000, v125
	v_lshlrev_b32_e32 v128, 16, v125
	v_pk_mul_f32 v[124:125], v[130:131], v[128:129]
	s_nop 0
	v_cvt_pk_bf16_f32 v141, v124, v125
	v_and_b32_e32 v125, 0xffff0000, v132
	v_lshlrev_b32_e32 v124, 16, v132
	s_waitcnt lgkmcnt(0)
	v_pk_mul_f32 v[72:73], v[72:73], v[124:125]
	s_nop 0
	v_cvt_pk_bf16_f32 v142, v72, v73
	v_and_b32_e32 v73, 0xffff0000, v133
	v_lshlrev_b32_e32 v72, 16, v133
	v_pk_mul_f32 v[72:73], v[74:75], v[72:73]
	ds_read_b64_tr_b16 v[124:125], v178 offset:34816
	ds_read_b64_tr_b16 v[136:137], v178 offset:34848
	ds_read_b64_tr_b16 v[132:133], v178 offset:34880
	ds_read_b64_tr_b16 v[128:129], v178 offset:34912
	ds_read_b64_tr_b16 v[138:139], v178 offset:35424
	ds_read_b64_tr_b16 v[134:135], v178 offset:35456
	ds_read_b64_tr_b16 v[130:131], v178 offset:35488
	v_cvt_pk_bf16_f32 v143, v72, v73
	s_waitcnt lgkmcnt(6)
	s_nop 0
	v_mfma_f32_16x16x32_bf16 v[72:75], v[140:143], v[124:127], v[112:115]
	s_waitcnt lgkmcnt(2)
	v_mfma_f32_16x16x32_bf16 v[116:119], v[140:143], v[136:139], v[116:119]
	s_waitcnt lgkmcnt(1)
	v_mfma_f32_16x16x32_bf16 v[104:107], v[140:143], v[132:135], v[104:107]
	s_waitcnt lgkmcnt(0)
	v_mfma_f32_16x16x32_bf16 v[108:111], v[140:143], v[128:131], v[108:111]
	s_cbranch_vccnz .LBB0_682
	v_readlane_b32 s0, v245, 14
	v_readlane_b32 s1, v245, 15
	v_lshlrev_b32_e32 v140, 16, v40
	v_and_b32_e32 v141, 0xffff0000, v40
	v_lshlrev_b32_e32 v114, 16, v41
	v_and_b32_e32 v115, 0xffff0000, v41
	v_lshlrev_b32_e32 v112, 16, v42
	v_and_b32_e32 v113, 0xffff0000, v42
	v_lshlrev_b32_e32 v40, 16, v43
	v_and_b32_e32 v41, 0xffff0000, v43
	s_andn2_b64 vcc, exec, s[0:1]
	s_mov_b64 s[0:1], -1
	s_cbranch_vccnz .LBB0_677
	s_add_i32 s0, s23, s88
	v_mov_b32_e32 v42, s0
	ds_read_b32 v42, v42
	v_lshl_add_u32 v43, v225, 2, s24
	ds_read_b128 v[178:181], v43
	ds_read_b128 v[182:185], v43 offset:16
	s_mov_b64 s[0:1], 0
	s_waitcnt lgkmcnt(2)
	v_sub_f32_e32 v42, v161, v42
	v_mul_f32_e32 v42, 0x3fb8aa3b, v42
	v_exp_f32_e32 v42, v42
	s_nop 0
	v_pk_mul_f32 v[142:143], v[42:43], v[140:141] op_sel_hi:[0,1]
	v_pk_mul_f32 v[186:187], v[42:43], v[114:115] op_sel_hi:[0,1]
	v_pk_mul_f32 v[188:189], v[42:43], v[112:113] op_sel_hi:[0,1]
	v_pk_mul_f32 v[190:191], v[42:43], v[40:41] op_sel_hi:[0,1]
	s_waitcnt lgkmcnt(1)
	v_pk_mul_f32 v[42:43], v[178:179], v[142:143]
	v_pk_mul_f32 v[142:143], v[180:181], v[186:187]
	s_waitcnt lgkmcnt(0)
	v_pk_mul_f32 v[178:179], v[188:189], v[182:183]
	v_pk_mul_f32 v[180:181], v[190:191], v[184:185]

; __device__ __forceinline__ void ssd_item(const Params& P, const int pass, const int item, const int wvi) {
;     ...
; #pragma unroll
;     for (int kk = 0; kk < 4; ++kk) {
;       const int s0 = kk * 32 + fq * 8;
;       bf16x8 xf[4];
; #pragma unroll
;       for (int pt = 0; pt < 4; ++pt) {
;         const u16* xa = Xs + (kk * 32 + fq * 8 + (fr >> 2)) * LDX + pt * 16 + (fr & 3) * 4;
;         xf[pt] = cat8(ldtr(xa), ldtr(xa + 4 * LDX));
;       }
;       {
;         const u16* ba = Bs + (kk * 32 + fq * 8 + (fr >> 2)) * LDP + w * 16 + (fr & 3) * 4;
;         const s16x4 b0 = ldtr(ba), b1 = ldtr(ba + 4 * LDP);
;         const float4 wa = *(const float4*)(fww + s0), wb = *(const float4*)(fww + s0 + 4);
;         const bf16x8 af = pack8(bf2f((u16)b0[0]) * wa.x, bf2f((u16)b0[1]) * wa.y, bf2f((u16)b0[2]) * wa.z, bf2f((u16)b0[3]) * wa.w,
;                                 bf2f((u16)b1[0]) * wb.x, bf2f((u16)b1[1]) * wb.y, bf2f((u16)b1[2]) * wb.z, bf2f((u16)b1[3]) * wb.w);
; #pragma unroll
;         for (int pt = 0; pt < 4; ++pt) st[pt] = __builtin_amdgcn_mfma_f32_16x16x32_bf16(af, xf[pt], st[pt], 0, 0, 0);
;       }
;       if (kk >= kk_lo && kk <= kk_hi) {
;         const uint4 gq = (kk == 0) ? gq0 : (kk == 1) ? gq1 : (kk == 2) ? gq2 : gq3;
;         const float gv[8] = {bflo(gq.x), bfhi(gq.x), bflo(gq.y), bfhi(gq.y), bflo(gq.z), bfhi(gq.z), bflo(gq.w), bfhi(gq.w)};
;         float mv[8];
;         if (kk == (it >> 1)) {
;           const float4 ca = *(const float4*)(fcum + s0), cb = *(const float4*)(fcum + s0 + 4);
;           const float4 da = *(const float4*)(fdt + s0), db = *(const float4*)(fdt + s0 + 4);
;           const float cs[8] = {ca.x, ca.y, ca.z, ca.w, cb.x, cb.y, cb.z, cb.w};
;           const float ds[8] = {da.x, da.y, da.z, da.w, db.x, db.y, db.z, db.w};
; #pragma unroll
;           for (int e = 0; e < 8; ++e) {
;             const int ss = s0 + e;
;             const bool ok = dir ? (ss >= ii) : (ss <= ii);
;             mv[e] = ok ? gv[e] * __expf(cum_i - cs[e]) * ds[e] : 0.f;
;           }
;         } else {
;           const float ai = __expf(cum_i - fcum[dir ? kk * 32 : kk * 32 + 31]);
;           const float4 ea = *(const float4*)(fee + s0), eb = *(const float4*)(fee + s0 + 4);
;           mv[0] = gv[0] * ai * ea.x; mv[1] = gv[1] * ai * ea.y; mv[2] = gv[2] * ai * ea.z; mv[3] = gv[3] * ai * ea.w;
.LBB0_682:
	global_load_dwordx4 v[16:19], v251, s[98:99]
	global_load_dwordx4 v[20:23], v252, s[98:99]
	ds_read_b128 v[40:43], v234 offset:53376
	ds_read_b128 v[112:115], v234 offset:57728
	ds_read_b128 v[128:131], v234 offset:62080
	ds_read_b128 v[132:135], v236 offset:53376
	v_add_u32_e32 v140, v235, v230
	v_lshl_add_u32 v124, v229, 2, s25
	s_waitcnt lgkmcnt(3)
	v_mfma_f32_16x16x32_bf16 v[76:79], v[40:43], v[28:31], v[76:79]
	ds_read_b64_tr_b16 v[126:127], v140 offset:35392
	s_andn2_b64 vcc, exec, s[96:97]
	s_waitcnt lgkmcnt(3)
	v_mfma_f32_16x16x32_bf16 v[40:43], v[112:115], v[28:31], v[120:123]
	v_add_u32_e32 v114, v233, v231
	ds_read_b64_tr_b16 v[112:113], v114
	ds_read_b64_tr_b16 v[114:115], v114 offset:1088
	s_waitcnt lgkmcnt(1)
	v_and_b32_e32 v125, 0xffff0000, v112
	v_mfma_f32_16x16x32_bf16 v[120:123], v[128:131], v[28:31], v[100:103]
	s_nop 2
	ds_read_b128 v[100:103], v124
	v_mfma_f32_16x16x32_bf16 v[28:31], v[132:135], v[28:31], v[36:39]
	s_nop 2
	ds_read_b128 v[36:39], v124 offset:16
	v_lshlrev_b32_e32 v124, 16, v112
	s_waitcnt lgkmcnt(1)
	v_pk_mul_f32 v[100:101], v[100:101], v[124:125]
	s_nop 0
	v_cvt_pk_bf16_f32 v136, v100, v101
	v_and_b32_e32 v101, 0xffff0000, v113
	v_lshlrev_b32_e32 v100, 16, v113
	v_pk_mul_f32 v[100:101], v[102:103], v[100:101]
	s_nop 0
	v_cvt_pk_bf16_f32 v137, v100, v101
	v_and_b32_e32 v101, 0xffff0000, v114
	v_lshlrev_b32_e32 v100, 16, v114
	s_waitcnt lgkmcnt(0)
	v_pk_mul_f32 v[36:37], v[36:37], v[100:101]
	s_nop 0
	v_cvt_pk_bf16_f32 v138, v36, v37
	v_and_b32_e32 v37, 0xffff0000, v115
	v_lshlrev_b32_e32 v36, 16, v115
	v_pk_mul_f32 v[36:37], v[38:39], v[36:37]
	s_nop 0
	v_cvt_pk_bf16_f32 v139, v36, v37
	ds_read_b64_tr_b16 v[124:125], v140 offset:34816
	ds_read_b64_tr_b16 v[132:133], v140 offset:34848
	ds_read_b64_tr_b16 v[128:129], v140 offset:34880
	ds_read_b64_tr_b16 v[36:37], v140 offset:34912
	ds_read_b64_tr_b16 v[134:135], v140 offset:35424
	ds_read_b64_tr_b16 v[130:131], v140 offset:35456
	ds_read_b64_tr_b16 v[38:39], v140 offset:35488
	s_waitcnt lgkmcnt(6)
	v_mfma_f32_16x16x32_bf16 v[112:115], v[136:139], v[124:127], v[72:75]
	s_waitcnt lgkmcnt(2)
	v_mfma_f32_16x16x32_bf16 v[100:103], v[136:139], v[132:135], v[116:119]
	s_waitcnt lgkmcnt(1)
	v_mfma_f32_16x16x32_bf16 v[104:107], v[136:139], v[128:131], v[104:107]
	s_waitcnt lgkmcnt(0)
	v_mfma_f32_16x16x32_bf16 v[108:111], v[136:139], v[36:39], v[108:111]
	s_cbranch_vccnz .LBB0_690
	v_readlane_b32 s0, v245, 17
	v_readlane_b32 s1, v245, 18
	v_lshlrev_b32_e32 v116, 16, v32
	v_and_b32_e32 v117, 0xffff0000, v32
	v_lshlrev_b32_e32 v74, 16, v33
	v_and_b32_e32 v75, 0xffff0000, v33
	v_lshlrev_b32_e32 v72, 16, v34
	v_and_b32_e32 v73, 0xffff0000, v34
	v_lshlrev_b32_e32 v32, 16, v35
	v_and_b32_e32 v33, 0xffff0000, v35
	s_andn2_b64 vcc, exec, s[0:1]
	s_mov_b64 s[0:1], -1
	s_cbranch_vccnz .LBB0_685
	s_add_i32 s0, s23, s89
	v_mov_b32_e32 v34, s0
	ds_read_b32 v34, v34
	v_lshl_add_u32 v35, v229, 2, s24
	ds_read_b128 v[136:139], v35
	ds_read_b128 v[140:143], v35 offset:16
	s_mov_b64 s[0:1], 0
	s_waitcnt lgkmcnt(2)
	v_sub_f32_e32 v34, v161, v34
	v_mul_f32_e32 v34, 0x3fb8aa3b, v34
	v_exp_f32_e32 v34, v34
	s_nop 0
	v_pk_mul_f32 v[118:119], v[34:35], v[116:117] op_sel_hi:[0,1]
	v_pk_mul_f32 v[178:179], v[34:35], v[74:75] op_sel_hi:[0,1]
	v_pk_mul_f32 v[180:181], v[34:35], v[72:73] op_sel_hi:[0,1]
	v_pk_mul_f32 v[182:183], v[34:35], v[32:33] op_sel_hi:[0,1]
	s_waitcnt lgkmcnt(1)
	v_pk_mul_f32 v[34:35], v[136:137], v[118:119]
	v_pk_mul_f32 v[118:119], v[138:139], v[178:179]
	s_waitcnt lgkmcnt(0)
	v_pk_mul_f32 v[136:137], v[180:181], v[140:141]
	v_pk_mul_f32 v[138:139], v[182:183], v[142:143]

; __device__ __forceinline__ void ssd_item(const Params& P, const int pass, const int item, const int wvi) {
;     ...
;     SSD_ISSUE((c + 1 < nch) ? (c + 1) : c);
;     ...
;       {
;         const bf16x8 cfk = (kk == 0) ? cf0 : (kk == 1) ? cf1 : (kk == 2) ? cf2 : cf3;
; #pragma unroll
;         for (int pt = 0; pt < 4; ++pt) {
;           const bf16x8 sf = *(const bf16x8*)(Sb + (pt * 16 + fr) * LDP + kk * 32 + fq * 8);
;           y2[pt] = __builtin_amdgcn_mfma_f32_16x16x32_bf16(sf, cfk, y2[pt], 0, 0, 0);
;         }
;       }
;     }
;     {
;       const float ec = __expf(cum_i);
; #pragma unroll
;       for (int pt = 0; pt < 4; ++pt) {
;         yp[pt][0] = pk2(y1[pt][0] + ec * y2[pt][0], y1[pt][1] + ec * y2[pt][1]);
;         yp[pt][1] = pk2(y1[pt][2] + ec * y2[pt][2], y1[pt][3] + ec * y2[pt][3]);
;       }
;     }
.LBB0_690:
	ds_read_b128 v[32:35], v234 offset:53440
	ds_read_b128 v[36:39], v234 offset:57792
	s_add_i32 s93, s93, -1
	s_cmp_lg_u32 s35, s34
	s_waitcnt lgkmcnt(0)
	v_mfma_f32_16x16x32_bf16 v[36:39], v[36:39], v[24:27], v[40:43]
	s_nop 2
	ds_read_b128 v[40:43], v234 offset:62144
	ds_read_b128 v[72:75], v236 offset:53440
	v_mfma_f32_16x16x32_bf16 v[32:35], v[32:35], v[24:27], v[76:79]
	s_waitcnt lgkmcnt(1)
	v_mfma_f32_16x16x32_bf16 v[40:43], v[40:43], v[24:27], v[120:123]
	s_waitcnt lgkmcnt(0)
	v_mfma_f32_16x16x32_bf16 v[24:27], v[72:75], v[24:27], v[28:31]
	s_nop 2
	v_mul_f32_e32 v28, 0x3fb8aa3b, v161
	v_exp_f32_e32 v28, v28
	s_nop 0
	v_pk_fma_f32 v[30:31], v[28:29], v[32:33], v[96:97] op_sel_hi:[0,1,1]
	v_cvt_pk_bf16_f32 v96, v30, v31
	v_pk_fma_f32 v[30:31], v[28:29], v[34:35], v[98:99] op_sel_hi:[0,1,1]
	v_cvt_pk_bf16_f32 v97, v30, v31
	v_pk_fma_f32 v[30:31], v[28:29], v[36:37], v[92:93] op_sel_hi:[0,1,1]
	v_cvt_pk_bf16_f32 v92, v30, v31
	v_pk_fma_f32 v[30:31], v[28:29], v[38:39], v[94:95] op_sel_hi:[0,1,1]
	v_cvt_pk_bf16_f32 v93, v30, v31
	v_pk_fma_f32 v[30:31], v[28:29], v[40:41], v[88:89] op_sel_hi:[0,1,1]
	v_pk_fma_f32 v[24:25], v[28:29], v[24:25], v[84:85] op_sel_hi:[0,1,1]
	v_cvt_pk_bf16_f32 v88, v30, v31
	v_pk_fma_f32 v[30:31], v[28:29], v[42:43], v[90:91] op_sel_hi:[0,1,1]
	v_cvt_pk_bf16_f32 v90, v24, v25
	v_pk_fma_f32 v[24:25], v[28:29], v[26:27], v[86:87] op_sel_hi:[0,1,1]
	v_cvt_pk_bf16_f32 v89, v30, v31
	v_cvt_pk_bf16_f32 v91, v24, v25
	s_cbranch_scc0 .LBB0_438
	s_waitcnt vmcnt(6)
	v_mov_b64_e32 v[74:75], v[62:63]
	v_mov_b64_e32 v[36:37], v[44:45]
	v_mov_b64_e32 v[28:29], v[48:49]
	s_waitcnt vmcnt(6)
	v_mov_b64_e32 v[24:25], v[52:53]
	v_mov_b64_e32 v[72:73], v[60:61]
	v_mov_b64_e32 v[38:39], v[46:47]
	v_mov_b64_e32 v[30:31], v[50:51]
	v_mov_b64_e32 v[26:27], v[54:55]
	s_mov_b32 s23, s35
	v_mov_b64_e32 v[32:33], v[80:81]
	v_mov_b64_e32 v[34:35], v[82:83]
	v_mov_b64_e32 v[40:41], v[68:69]
	v_mov_b64_e32 v[42:43], v[70:71]
	v_mov_b64_e32 v[76:77], v[64:65]
	v_mov_b64_e32 v[78:79], v[66:67]
	v_mov_b64_e32 v[84:85], v[56:57]
	v_mov_b64_e32 v[86:87], v[58:59]
	s_branch .LBB0_647

; __global__ void __launch_bounds__(NTHR) fwd_megakernel(const Params P) {
	.amdhsa_kernel _Z14fwd_megakernel6Params
		.amdhsa_group_segment_fixed_size 32
		.amdhsa_private_segment_fixed_size 0
		.amdhsa_kernarg_size 688
		.amdhsa_user_sgpr_count 2
		.amdhsa_user_sgpr_dispatch_ptr 0
		.amdhsa_user_sgpr_queue_ptr 0
		.amdhsa_user_sgpr_kernarg_segment_ptr 1
		.amdhsa_user_sgpr_dispatch_id 0
		.amdhsa_user_sgpr_kernarg_preload_length 0
		.amdhsa_user_sgpr_kernarg_preload_offset 0
		.amdhsa_user_sgpr_private_segment_size 0
		.amdhsa_uses_dynamic_stack 0
		.amdhsa_enable_private_segment 0
		.amdhsa_system_sgpr_workgroup_id_x 1
		.amdhsa_system_sgpr_workgroup_id_y 0
		.amdhsa_system_sgpr_workgroup_id_z 0
		.amdhsa_system_sgpr_workgroup_info 0
		.amdhsa_system_vgpr_workitem_id 2
		.amdhsa_next_free_vgpr 256
		.amdhsa_next_free_sgpr 102
		.amdhsa_accum_offset 256
		.amdhsa_reserve_vcc 1
		.amdhsa_float_round_mode_32 0
		.amdhsa_float_round_mode_16_64 0
		.amdhsa_float_denorm_mode_32 3
		.amdhsa_float_denorm_mode_16_64 3
		.amdhsa_dx10_clamp 1
		.amdhsa_ieee_mode 1
		.amdhsa_fp16_overflow 0
		.amdhsa_tg_split 0
		.amdhsa_exception_fp_ieee_invalid_op 0
		.amdhsa_exception_fp_denorm_src 0
		.amdhsa_exception_fp_ieee_div_zero 0
		.amdhsa_exception_fp_ieee_overflow 0
		.amdhsa_exception_fp_ieee_underflow 0
		.amdhsa_exception_fp_ieee_inexact 0
		.amdhsa_exception_int_div_zero 0
	.end_amdhsa_kernel

; __global__ void __launch_bounds__(NTHR) fwd_megakernel(const Params P) {
amdhsa.kernels:
  - .agpr_count:     0
    .args:
      - .offset:         0
        .size:           432
        .value_kind:     by_value
      - .offset:         432
        .size:           4
        .value_kind:     hidden_block_count_x
      - .offset:         436
        .size:           4
        .value_kind:     hidden_block_count_y
      - .offset:         440
        .size:           4
        .value_kind:     hidden_block_count_z
      - .offset:         444
        .size:           2
        .value_kind:     hidden_group_size_x
      - .offset:         446
        .size:           2
        .value_kind:     hidden_group_size_y
      - .offset:         448
        .size:           2
        .value_kind:     hidden_group_size_z
      - .offset:         450
        .size:           2
        .value_kind:     hidden_remainder_x
      - .offset:         452
        .size:           2
        .value_kind:     hidden_remainder_y
      - .offset:         454
        .size:           2
        .value_kind:     hidden_remainder_z
      - .offset:         472
        .size:           8
        .value_kind:     hidden_global_offset_x
      - .offset:         480
        .size:           8
        .value_kind:     hidden_global_offset_y
      - .offset:         488
        .size:           8
        .value_kind:     hidden_global_offset_z
      - .offset:         496
        .size:           2
        .value_kind:     hidden_grid_dims
      - .offset:         520
        .size:           8
        .value_kind:     hidden_multigrid_sync_arg
      - .offset:         552
        .size:           4
        .value_kind:     hidden_dynamic_lds_size
    .group_segment_fixed_size: 32
    .kernarg_segment_align: 8
    .kernarg_segment_size: 688
    .language:       OpenCL C
    .language_version:
      - 2
      - 0
    .max_flat_workgroup_size: 512
    .name:           _Z14fwd_megakernel6Params
    .private_segment_fixed_size: 0
    .sgpr_count:     108
    .sgpr_spill_count: 284
    .symbol:         _Z14fwd_megakernel6Params.kd
    .uniform_work_group_size: 1
    .uses_dynamic_stack: false
    .vgpr_count:     256
    .vgpr_spill_count: 0
    .wavefront_size: 64
